# GEMM tile prologue: the wait for the first K-step DMA moved behind the accumulator zero-init (just before the barrier) so the 96 zeroing moves overlap the DMA latency
# speedup vs baseline: 1.0046x; 1.0046x over previous
.LBB0_485:
	s_lshl_b32 s8, s20, 6
	s_mov_b32 s9, 0
	s_lshl_b32 s10, s28, 6
	s_mov_b32 s11, 0
	s_and_b32 s76, s92, 63
	s_mulk_i32 s76, 0xc0
	v_add_u32_e32 v8, s76, v136
	v_ashrrev_i32_e32 v9, 31, v8
	s_lshl_b32 s77, s84, 8
	s_waitcnt vmcnt(3)
	v_mul_lo_u32 v10, s20, v9
	v_mul_lo_u32 v11, s21, v8
	v_mad_u64_u32 v[8:9], s[86:87], s20, v8, 0
	v_add3_u32 v9, v9, v10, v11
	v_add_u32_e32 v10, s77, v136
	v_mad_u64_u32 v[12:13], s[86:87], v10, s28, 0
	v_ashrrev_i32_e32 v11, 31, v10
	s_waitcnt vmcnt(2)
	v_mov_b32_e32 v14, v13
	v_mad_u64_u32 v[14:15], s[86:87], v11, s28, v[14:15]
	v_lshl_add_u64 v[8:9], v[8:9], 1, s[56:57]
	v_mov_b32_e32 v13, v14
	v_readfirstlane_b32 s84, v137
	v_add_u32_e32 v14, 0x2000, v137
	v_lshl_add_u64 v[8:9], v[8:9], 0, v[0:1]
	s_mov_b32 m0, s84
	s_lshl_b64 s[86:87], s[20:21], 7
	v_readfirstlane_b32 s84, v14
	v_add_u32_e32 v14, 0x4000, v137
	global_load_lds_dwordx4 v[8:9], off
	v_lshl_add_u64 v[8:9], v[8:9], 0, s[86:87]
	s_mov_b32 m0, s84
	v_readfirstlane_b32 s84, v14
	v_lshl_add_u64 v[12:13], v[12:13], 1, s[2:3]
	global_load_lds_dwordx4 v[8:9], off
	v_lshl_add_u64 v[8:9], v[8:9], 0, s[86:87]
	s_mov_b32 m0, s84
	s_lshl_b64 s[86:87], s[28:29], 7
	global_load_lds_dwordx4 v[8:9], off
	v_lshl_add_u64 v[8:9], v[12:13], 0, v[0:1]
	v_add_u32_e32 v12, 0x6000, v137
	s_and_b32 s34, s79, 63
	v_readfirstlane_b32 s84, v12
	v_add_u32_e32 v12, 0x8000, v137
	s_mov_b32 m0, s84
	v_readfirstlane_b32 s84, v12
	v_add_u32_e32 v12, 0xa000, v137
	global_load_lds_dwordx4 v[8:9], off
	v_lshl_add_u64 v[8:9], v[8:9], 0, s[86:87]
	s_mov_b32 m0, s84
	v_readfirstlane_b32 s84, v12
	v_add_u32_e32 v12, 0xc000, v137
	global_load_lds_dwordx4 v[8:9], off
	v_lshl_add_u64 v[8:9], v[8:9], 0, s[86:87]
	s_mov_b32 m0, s84
	v_readfirstlane_b32 s84, v12
	global_load_lds_dwordx4 v[8:9], off
	v_lshl_add_u64 v[8:9], v[8:9], 0, s[86:87]
	s_mov_b32 m0, s84
	s_mulk_i32 s34, 0xc0
	global_load_lds_dwordx4 v[8:9], off
	s_mov_b64 s[4:5], 0x80
	v_lshl_add_u64 v[8:9], s[56:57], 0, v[98:99]
	v_add_u32_e32 v2, s34, v136
	v_lshl_add_u64 v[8:9], v[8:9], 0, s[4:5]
	s_lshl_b32 s86, s20, 1
	v_ashrrev_i32_e32 v3, 31, v2
	v_mad_u64_u32 v[100:101], s[56:57], s86, v2, v[8:9]
	v_lshlrev_b64 v[4:5], 1, v[2:3]
	s_mov_b64 s[6:7], 0x100
	s_lshr_b64 s[56:57], s[20:21], 31
	v_lshl_add_u64 v[6:7], v[4:5], 0, s[6:7]
	v_mul_lo_u32 v2, s56, v2
	v_mul_lo_u32 v3, s86, v3
	v_lshl_add_u64 v[4:5], v[4:5], 0, s[4:5]
	v_add3_u32 v101, v2, v101, v3
	v_mul_lo_u32 v2, s20, v7
	v_mul_lo_u32 v3, s21, v6
	v_mad_u64_u32 v[102:103], s[56:57], s20, v6, v[8:9]
	v_add3_u32 v103, v3, v103, v2
	v_mul_lo_u32 v2, s20, v5
	v_mul_lo_u32 v3, s21, v4
	v_mad_u64_u32 v[104:105], s[20:21], s20, v4, v[8:9]
	v_add3_u32 v105, v3, v105, v2
	v_lshl_add_u64 v[2:3], s[2:3], 0, v[98:99]
	v_lshl_add_u64 v[2:3], v[2:3], 0, s[4:5]
	v_lshlrev_b64 v[4:5], 1, v[10:11]
	v_mad_u64_u32 v[106:107], s[2:3], v4, s28, v[2:3]
	v_alignbit_b32 v7, v11, v10, 31
	v_mov_b32_e32 v6, v107
	v_mad_u64_u32 v[6:7], s[2:3], v7, s28, v[6:7]
	v_mov_b32_e32 v107, v6
	v_lshl_add_u64 v[6:7], v[4:5], 0, s[6:7]
	v_mad_u64_u32 v[108:109], s[2:3], v6, s28, v[2:3]
	v_mov_b32_e32 v6, v109
	v_mad_u64_u32 v[6:7], s[2:3], v7, s28, v[6:7]
	s_mov_b64 s[2:3], 0x180
	v_mov_b32_e32 v109, v6
	v_lshl_add_u64 v[6:7], v[4:5], 0, s[2:3]
	v_lshl_add_u64 v[4:5], v[4:5], 0, s[4:5]
	v_mad_u64_u32 v[110:111], s[2:3], v6, s28, v[2:3]
	v_mad_u64_u32 v[112:113], s[2:3], v4, s28, v[2:3]
	v_mov_b32_e32 v6, v111
	v_mov_b32_e32 v2, v113
	v_mad_u64_u32 v[6:7], s[2:3], v7, s28, v[6:7]
	v_mad_u64_u32 v[2:3], s[2:3], v5, s28, v[2:3]
	v_mov_b32_e32 v113, v2
	s_lshl_b64 s[2:3], s[28:29], 1
	v_mov_b32_e32 v2, 0
	s_mov_b32 s34, 1
	s_lshr_b32 s84, s28, 6
	v_mov_b32_e32 v111, v6
	s_and_b32 s20, s2, 0xffffff80
	s_mov_b64 s[2:3], 0
	v_mov_b32_e32 v3, v2
	v_mov_b32_e32 v4, v2
	v_mov_b32_e32 v5, v2
	v_mov_b32_e32 v6, v2
	v_mov_b32_e32 v7, v2
	v_mov_b32_e32 v8, v2
	v_mov_b32_e32 v9, v2
	v_mov_b32_e32 v10, v2
	v_mov_b32_e32 v11, v2
	v_mov_b32_e32 v12, v2
	v_mov_b32_e32 v13, v2
	v_mov_b32_e32 v14, v2
	v_mov_b32_e32 v15, v2
	v_mov_b32_e32 v16, v2
	v_mov_b32_e32 v17, v2
	v_mov_b32_e32 v18, v2
	v_mov_b32_e32 v19, v2
	v_mov_b32_e32 v20, v2
	v_mov_b32_e32 v21, v2
	v_mov_b32_e32 v22, v2
	v_mov_b32_e32 v23, v2
	v_mov_b32_e32 v24, v2
	v_mov_b32_e32 v25, v2
	v_mov_b32_e32 v26, v2
	v_mov_b32_e32 v27, v2
	v_mov_b32_e32 v28, v2
	v_mov_b32_e32 v29, v2
	v_mov_b32_e32 v30, v2
	v_mov_b32_e32 v31, v2
	v_mov_b32_e32 v32, v2
	v_mov_b32_e32 v33, v2
	v_mov_b32_e32 v34, v2
	v_mov_b32_e32 v35, v2
	v_mov_b32_e32 v36, v2
	v_mov_b32_e32 v37, v2
	v_mov_b32_e32 v38, v2
	v_mov_b32_e32 v39, v2
	v_mov_b32_e32 v40, v2
	v_mov_b32_e32 v41, v2
	v_mov_b32_e32 v42, v2
	v_mov_b32_e32 v43, v2
	v_mov_b32_e32 v44, v2
	v_mov_b32_e32 v45, v2
	v_mov_b32_e32 v46, v2
	v_mov_b32_e32 v47, v2
	v_mov_b32_e32 v48, v2
	v_mov_b32_e32 v49, v2
	v_mov_b32_e32 v50, v2
	v_mov_b32_e32 v51, v2
	v_mov_b32_e32 v52, v2
	v_mov_b32_e32 v53, v2
	v_mov_b32_e32 v54, v2
	v_mov_b32_e32 v55, v2
	v_mov_b32_e32 v56, v2
	v_mov_b32_e32 v57, v2
	v_mov_b32_e32 v58, v2
	v_mov_b32_e32 v59, v2
	v_mov_b32_e32 v60, v2
	v_mov_b32_e32 v61, v2
	v_mov_b32_e32 v62, v2
	v_mov_b32_e32 v63, v2
	v_mov_b32_e32 v64, v2
	v_mov_b32_e32 v65, v2
	v_mov_b32_e32 v66, v2
	v_mov_b32_e32 v67, v2
	v_mov_b32_e32 v68, v2
	v_mov_b32_e32 v69, v2
	v_mov_b32_e32 v70, v2
	v_mov_b32_e32 v71, v2
	v_mov_b32_e32 v72, v2
	v_mov_b32_e32 v73, v2
	v_mov_b32_e32 v74, v2
	v_mov_b32_e32 v75, v2
	v_mov_b32_e32 v76, v2
	v_mov_b32_e32 v77, v2
	v_mov_b32_e32 v78, v2
	v_mov_b32_e32 v79, v2
	v_mov_b32_e32 v80, v2
	v_mov_b32_e32 v81, v2
	v_mov_b32_e32 v82, v2
	v_mov_b32_e32 v83, v2
	v_mov_b32_e32 v84, v2
	v_mov_b32_e32 v85, v2
	v_mov_b32_e32 v86, v2
	v_mov_b32_e32 v87, v2
	v_mov_b32_e32 v88, v2
	v_mov_b32_e32 v89, v2
	v_mov_b32_e32 v90, v2
	v_mov_b32_e32 v91, v2
	v_mov_b32_e32 v92, v2
	v_mov_b32_e32 v93, v2
	v_mov_b32_e32 v94, v2
	v_mov_b32_e32 v95, v2
	v_mov_b32_e32 v96, v2
	v_mov_b32_e32 v97, v2
	s_waitcnt vmcnt(0)
	s_waitcnt lgkmcnt(0)
	s_barrier
	v_readfirstlane_b32 s4, v137
	v_lshrrev_b32_e32 v172, 6, v203
	s_nop 0
	v_readfirstlane_b32 s12, v172
	v_and_b32_e32 v172, 63, v203
	v_lshrrev_b32_e32 v173, 6, v203
	v_and_b32_e32 v174, 15, v172
	v_lshrrev_b32_e32 v175, 4, v172
	v_bfe_u32 v176, v172, 1, 3
	v_xor_b32_e32 v177, v175, v176
	v_lshlrev_b32_e32 v177, 4, v177
	v_or_b32_e32 v175, 4, v175
	v_xor_b32_e32 v175, v175, v176
	v_lshlrev_b32_e32 v175, 4, v175
	v_lshrrev_b32_e32 v176, 2, v173
	v_and_b32_e32 v173, 3, v173
	v_mul_u32_u24_e32 v176, 0x60, v176
	v_add_u32_e32 v176, v176, v174
	v_lshlrev_b32_e32 v176, 7, v176
	v_lshl_add_u32 v173, v173, 6, v174
	v_lshlrev_b32_e32 v173, 7, v173
	v_add_u32_e32 v173, 0x6020, v173
	v_add_u32_e32 v176, 32, v176
	v_add_u32_e32 v204, v176, v177
	v_add_u32_e32 v205, v176, v175
	v_add_u32_e32 v206, v173, v177
	v_add_u32_e32 v207, v173, v175
	s_cmp_ge_u32 s34, s84
	s_cbranch_scc1 .Lgk_last
